# CMP GEMM: the zero half of the padded weight tile is no longer staged (8 LDS-DMA loads per iteration dropped, counted waits re-derived), stray prologue vmcnt(0) removed
# baseline (speedup 1.0000x reference)
.LBB0_856:
	s_andn2_b64 vcc, exec, s[0:1]
	s_cbranch_vccnz .LBB0_1134
	v_bfe_i32 v2, v8, 27, 1
	v_lshlrev_b32_e32 v0, 4, v8
	v_lshrrev_b32_e32 v2, 22, v2
	v_add_u32_e32 v2, v0, v2
	v_and_b32_e32 v2, 0xfffffc00, v2
	v_sub_u32_e32 v2, v0, v2
	s_waitcnt lgkmcnt(0)
	v_ashrrev_i32_e32 v1, 31, v8
	v_lshrrev_b32_e32 v3, 4, v2
	v_lshrrev_b32_e32 v1, 26, v1
	v_bitop3_b32 v2, v3, v2, 32 bitop3:0x6c
	v_add_u32_e32 v1, v8, v1
	v_ashrrev_i32_e32 v4, 31, v2
	v_ashrrev_i32_e32 v1, 6, v1
	v_lshrrev_b32_e32 v4, 26, v4
	v_lshlrev_b32_e32 v3, 3, v1
	v_add_u32_e32 v4, v2, v4
	v_lshlrev_b32_e32 v1, 5, v1
	v_and_b32_e32 v3, -16, v3
	v_ashrrev_i32_e32 v5, 6, v4
	v_and_b32_e32 v9, 32, v1
	v_and_b32_e32 v1, 0xc0, v4
	v_add_u32_e32 v3, v5, v3
	v_sub_u32_e32 v1, v2, v1
	v_mov_b32_e32 v2, 1
	v_and_b32_e32 v5, 3, v5
	s_mov_b32 s1, 0xfffe0
	v_ashrrev_i16_sdwa v1, v2, sext(v1) dst_sel:DWORD dst_unused:UNUSED_PAD src0_sel:DWORD src1_sel:BYTE_0
	v_lshlrev_b32_e32 v4, 1, v3
	v_lshrrev_b32_e32 v6, 2, v3
	v_and_or_b32 v5, v3, s1, v5
	s_movk_i32 s2, 0x6000
	v_lshlrev_b32_e32 v3, 6, v3
	v_bfe_i32 v10, v1, 0, 16
	v_mul_lo_u32 v11, v6, s2
	v_and_b32_e32 v12, 0xc0, v3
	v_add_u32_e32 v1, v9, v10
	v_and_b32_e32 v4, 24, v4
	v_and_b32_e32 v7, 4, v6
	v_or_b32_e32 v3, v11, v12
	v_or3_b32 v4, v5, v7, v4
	v_add_lshl_u32 v72, v3, v1, 1
	v_lshlrev_b32_e32 v1, 1, v1
	v_add_u32_e32 v0, 0x2000, v0
	v_lshl_add_u32 v74, v4, 12, v1
	v_ashrrev_i32_e32 v1, 31, v0
	v_lshrrev_b32_e32 v1, 22, v1
	v_add_u32_e32 v1, v0, v1
	v_ashrrev_i32_e32 v1, 10, v1
	v_mul_i32_i24_e32 v3, 0x400, v1
	v_sub_u32_e32 v0, v0, v3
	v_lshrrev_b32_e32 v3, 4, v0
	v_bitop3_b32 v0, v3, v0, 32 bitop3:0x6c
	v_ashrrev_i32_e32 v4, 31, v0
	v_lshrrev_b32_e32 v4, 26, v4
	v_lshlrev_b32_e32 v3, 3, v1
	v_add_u32_e32 v4, v0, v4
	v_lshlrev_b32_e32 v1, 5, v1
	v_and_b32_e32 v3, -16, v3
	v_ashrrev_i32_e32 v5, 6, v4
	v_and_b32_e32 v13, 32, v1
	v_and_b32_e32 v1, 0xc0, v4
	s_add_u32 s39, s44, 0x3080000
	v_add_u32_e32 v3, v5, v3
	v_sub_u32_e32 v0, v0, v1
	s_addc_u32 s40, s45, 0
	s_ashr_i32 s0, s38, 6
	v_ashrrev_i16_sdwa v0, v2, sext(v0) dst_sel:DWORD dst_unused:UNUSED_PAD src0_sel:DWORD src1_sel:BYTE_0
	v_lshrrev_b32_e32 v2, 2, v3
	v_and_b32_e32 v5, 3, v5
	s_ashr_i32 s31, s30, 31
	v_and_or_b32 v5, v3, s1, v5
	v_mul_lo_u32 v15, v2, s2
	s_ashr_i32 s1, s38, 8
	s_lshl_b32 s41, s0, 10
	s_lshl_b64 s[2:3], s[30:31], 9
	s_lshl_b64 s[6:7], s[30:31], 20
	s_add_u32 s36, s39, s6
	s_addc_u32 s37, s40, s7
	s_add_i32 s42, s41, 0
	s_add_i32 m0, s42, 0x10000
	v_and_b32_e32 v4, 4, v2
	v_lshlrev_b32_e32 v2, 6, v3
	s_mul_i32 s9, s70, 0x300000
	global_load_lds_dwordx4 v74, s[36:37]
	s_add_i32 m0, s42, 0x12000
	v_bfe_i32 v14, v0, 0, 16
	v_lshlrev_b32_e32 v1, 1, v3
	v_and_b32_e32 v16, 0xc0, v2
	s_mul_hi_i32 s8, s70, 0x300000
	s_add_u32 s6, s24, s9
	v_add_u32_e32 v0, v13, v14
	v_and_b32_e32 v1, 24, v1
	v_or_b32_e32 v2, v15, v16
	s_addc_u32 s7, s25, s8
	v_or3_b32 v1, v5, v4, v1
	v_add_lshl_u32 v76, v2, v0, 1
	v_lshlrev_b32_e32 v0, 1, v0
	s_add_u32 s34, s6, s2
	v_lshl_add_u32 v78, v1, 12, v0
	s_addc_u32 s35, s7, s3
	s_add_i32 s43, s42, 0x2000
	global_load_lds_dwordx4 v78, s[36:37]
	s_mov_b32 m0, s42
	s_add_u32 s2, s36, 0x80000
	global_load_lds_dwordx4 v72, s[34:35]
	s_mov_b32 m0, s43
	s_addc_u32 s3, s37, 0
	s_add_i32 s44, s42, 0x14000
	global_load_lds_dwordx4 v76, s[34:35]
	s_mov_b32 m0, s44
	s_add_i32 s45, s42, 0x16000
	s_mov_b32 m0, s45
	v_mov_b32_e32 v81, 0
	s_add_u32 s2, s34, 0x180000
	s_addc_u32 s3, s35, 0
	s_add_i32 s46, s42, 0x4000
	s_mov_b32 m0, s46
	s_add_i32 s47, s42, 0x6000
	global_load_lds_dwordx4 v72, s[2:3]
	s_mov_b32 m0, s47
	v_mov_b32_e32 v75, v81
	global_load_lds_dwordx4 v76, s[2:3]
	v_mov_b32_e32 v79, v81
	v_mov_b32_e32 v73, v81
	v_mov_b32_e32 v77, v81
	s_mov_b32 s48, 0
	s_mov_b32 s49, 0x10000
	v_lshl_add_u64 v[6:7], s[36:37], 0, v[74:75]
	v_lshl_add_u64 v[4:5], s[36:37], 0, v[78:79]
	s_mov_b32 s50, 0x12000
	v_lshl_add_u64 v[2:3], s[34:35], 0, v[72:73]
	v_lshl_add_u64 v[0:1], s[34:35], 0, v[76:77]
	s_cmp_lg_u32 s1, 1
	s_mov_b32 s51, 0x14000
	s_cbranch_scc1 .LBB0_859
	s_barrier
.LBB0_859:
	v_readlane_b32 s12, v235, 29
	v_readlane_b32 s13, v235, 30
	s_add_u32 s52, s12, 0x36040000
	s_addc_u32 s53, s13, 0
	s_lshl_b32 s0, s0, 5
	s_mov_b64 s[6:7], 0x80
	s_and_b32 s0, s0, 0x60
	s_add_i32 m0, s42, 0x18000
	v_lshl_add_u64 v[6:7], v[6:7], 0, s[6:7]
	s_lshl_b32 s10, s1, 13
	s_lshl_b32 s11, s0, 7
	s_waitcnt vmcnt(2)
	s_barrier
	global_load_lds_dwordx4 v[6:7], off
	v_lshl_add_u64 v[4:5], v[4:5], 0, s[6:7]
	s_add_i32 m0, s42, 0x1a000
	s_mov_b64 s[8:9], 0xc00
	s_add_i32 s54, s42, 0x8000
	s_add_i32 s55, s42, 0xa000
	global_load_lds_dwordx4 v[4:5], off
	v_lshl_add_u64 v[2:3], v[2:3], 0, s[8:9]
	s_mov_b32 m0, s54
	s_add_u32 s2, s36, 0x80080
	global_load_lds_dwordx4 v[2:3], off
	v_lshl_add_u64 v[0:1], v[0:1], 0, s[8:9]
	s_mov_b32 m0, s55
	s_addc_u32 s3, s37, 0
	s_add_i32 s56, s42, 0x1c000
	global_load_lds_dwordx4 v[0:1], off
	v_lshl_add_u64 v[0:1], s[2:3], 0, v[74:75]
	s_mov_b32 m0, s56
	s_add_i32 s57, s42, 0x1e000
	v_lshl_add_u64 v[0:1], s[2:3], 0, v[78:79]
	s_mov_b32 m0, s57
	v_readlane_b32 s14, v235, 31
	v_lshrrev_b32_e32 v1, 1, v8
	v_and_b32_e32 v1, 24, v1
	v_and_b32_e32 v0, 15, v8
	v_lshlrev_b32_e32 v2, 1, v1
	v_lshl_or_b32 v83, s1, 6, v0
	v_lshl_or_b32 v0, v0, 6, v2
	v_lshlrev_b32_e32 v2, 2, v8
	v_or_b32_e32 v82, s0, v1
	v_and_b32_e32 v2, 32, v2
	v_lshlrev_b32_e32 v80, 2, v82
	v_bitop3_b32 v3, v0, s10, v2 bitop3:0xde
	v_bitop3_b32 v94, v0, s11, v2 bitop3:0xde
	v_lshl_add_u64 v[0:1], s[12:13], 0, v[80:81]
	s_mov_b64 s[0:1], 0x3280000
	v_lshl_add_u64 v[84:85], v[0:1], 0, s[0:1]
	v_add3_u32 v0, v11, v12, v9
	s_waitcnt vmcnt(4)
	v_add_lshl_u32 v80, v0, v10, 1
	s_mov_b64 s[0:1], 0x180c00
	v_add3_u32 v0, v15, v16, v13
	v_readlane_b32 s15, v235, 32
	v_lshl_add_u64 v[86:87], v[80:81], 0, s[0:1]
	v_add_lshl_u32 v80, v0, v14, 1
	s_ashr_i32 s58, s66, 31
	s_ashr_i32 s59, s33, 31
	v_lshl_add_u64 v[88:89], v[80:81], 0, s[0:1]
	v_mov_b64_e32 v[90:91], 0x80
	v_mov_b64_e32 v[92:93], 0x7f
	s_add_i32 s60, 0, 0x10000
	v_add_u32_e32 v95, 0, v3
	s_mov_b32 s61, 0x3f200000
	s_mov_b32 s62, 0x3fb8aa3b
	s_mov_b32 s63, 0xc2ce8ed0
	s_mov_b32 s67, 0x42b17218
	v_mov_b32_e32 v96, 0x3ca908c9
	s_brev_b32 s68, -2
	s_mov_b64 s[10:11], 0x10000
	s_mov_b64 s[12:13], 0x12000
	s_mov_b64 s[14:15], 0x14000
	s_mov_b64 s[18:19], 0x16000
	v_mov_b32_e32 v97, 0x7f800000
	s_barrier
	s_branch .LBB0_861

.LBB0_870:
	v_add_u32_e32 v80, s60, v94
	ds_read_b128 v[8:11], v80
	ds_read_b128 v[16:19], v80 offset:1024
	ds_read_b128 v[98:101], v80 offset:2048
	ds_read_b128 v[102:105], v80 offset:3072
	s_and_b64 s[0:1], exec, s[0:1]
	s_cselect_b32 s1, s21, s78
	s_cselect_b32 s0, s31, s71
	v_lshl_add_u64 v[138:139], s[34:35], 0, v[86:87]
	s_add_i32 m0, s42, 0xc000
	ds_read_b128 v[106:109], v95
	ds_read_b128 v[110:113], v95 offset:1024
	ds_read_b128 v[114:117], v95 offset:2048
	ds_read_b128 v[118:121], v95 offset:3072
	ds_read_b128 v[122:125], v95 offset:4096
	ds_read_b128 v[126:129], v95 offset:5120
	ds_read_b128 v[130:133], v95 offset:6144
	ds_read_b128 v[134:137], v95 offset:7168
	global_load_lds_dwordx4 v[138:139], off
	v_lshl_add_u64 v[138:139], s[34:35], 0, v[88:89]
	s_add_i32 m0, s42, 0xe000
	s_nop 0
	global_load_lds_dwordx4 v[138:139], off
	s_waitcnt lgkmcnt(8)
	s_barrier
	s_waitcnt lgkmcnt(0)
	s_setprio 1
	s_waitcnt lgkmcnt(0)
	v_mfma_f32_16x16x32_bf16 v[68:71], v[8:11], v[106:109], v[68:71]
	v_mfma_f32_16x16x32_bf16 v[64:67], v[98:101], v[106:109], v[64:67]
	v_mfma_f32_16x16x32_bf16 v[60:63], v[8:11], v[114:117], v[60:63]
	v_mfma_f32_16x16x32_bf16 v[56:59], v[98:101], v[114:117], v[56:59]
	v_mfma_f32_16x16x32_bf16 v[52:55], v[8:11], v[122:125], v[52:55]
	v_mfma_f32_16x16x32_bf16 v[48:51], v[98:101], v[122:125], v[48:51]
	v_mfma_f32_16x16x32_bf16 v[44:47], v[8:11], v[130:133], v[44:47]
	v_mfma_f32_16x16x32_bf16 v[40:43], v[98:101], v[130:133], v[40:43]
	v_mfma_f32_16x16x32_bf16 v[68:71], v[16:19], v[110:113], v[68:71]
	v_mfma_f32_16x16x32_bf16 v[64:67], v[102:105], v[110:113], v[64:67]
	v_mfma_f32_16x16x32_bf16 v[60:63], v[16:19], v[118:121], v[60:63]
	v_mfma_f32_16x16x32_bf16 v[56:59], v[102:105], v[118:121], v[56:59]
	v_mfma_f32_16x16x32_bf16 v[52:55], v[16:19], v[126:129], v[52:55]
	v_mfma_f32_16x16x32_bf16 v[48:51], v[102:105], v[126:129], v[48:51]
	v_mfma_f32_16x16x32_bf16 v[44:47], v[16:19], v[134:137], v[44:47]
	v_mfma_f32_16x16x32_bf16 v[40:43], v[102:105], v[134:137], v[40:43]
	s_setprio 0
	s_barrier
	s_add_i32 s80, s60, s41
	v_lshl_add_u64 v[138:139], s[0:1], 0, v[74:75]
	s_mov_b32 m0, s80
	v_lshl_add_u64 v[140:141], s[0:1], 0, v[78:79]
	global_load_lds_dwordx4 v[138:139], off
	s_add_i32 m0, s80, 0x2000
	s_nop 0
	global_load_lds_dwordx4 v[140:141], off
	s_barrier
	s_waitcnt lgkmcnt(0)
	s_setprio 1
	s_setprio 0
	s_mov_b32 m0, s42
	v_lshl_add_u64 v[142:143], s[36:37], 0, v[72:73]
	s_barrier
	ds_read_b128 v[106:109], v95 offset:16384
	ds_read_b128 v[110:113], v95 offset:17408
	ds_read_b128 v[114:117], v95 offset:18432
	ds_read_b128 v[118:121], v95 offset:19456
	ds_read_b128 v[122:125], v95 offset:20480
	ds_read_b128 v[126:129], v95 offset:21504
	ds_read_b128 v[130:133], v95 offset:22528
	ds_read_b128 v[134:137], v95 offset:23552
	global_load_lds_dwordx4 v[142:143], off
	v_lshl_add_u64 v[144:145], s[36:37], 0, v[76:77]
	s_mov_b32 m0, s43
	s_nop 0
	global_load_lds_dwordx4 v[144:145], off
	s_barrier
	s_waitcnt lgkmcnt(0)
	s_setprio 1
	s_waitcnt lgkmcnt(0)
	v_mfma_f32_16x16x32_bf16 v[36:39], v[8:11], v[106:109], v[36:39]
	v_mfma_f32_16x16x32_bf16 v[32:35], v[98:101], v[106:109], v[32:35]
	v_mfma_f32_16x16x32_bf16 v[28:31], v[8:11], v[114:117], v[28:31]
	v_mfma_f32_16x16x32_bf16 v[24:27], v[98:101], v[114:117], v[24:27]
	v_mfma_f32_16x16x32_bf16 v[20:23], v[8:11], v[122:125], v[20:23]
	v_mfma_f32_16x16x32_bf16 v[12:15], v[98:101], v[122:125], v[12:15]
	v_mfma_f32_16x16x32_bf16 v[4:7], v[8:11], v[130:133], v[4:7]
	v_mfma_f32_16x16x32_bf16 v[0:3], v[98:101], v[130:133], v[0:3]
	v_mfma_f32_16x16x32_bf16 v[36:39], v[16:19], v[110:113], v[36:39]
	v_mfma_f32_16x16x32_bf16 v[32:35], v[102:105], v[110:113], v[32:35]
	v_mfma_f32_16x16x32_bf16 v[28:31], v[16:19], v[118:121], v[28:31]
	v_mfma_f32_16x16x32_bf16 v[24:27], v[102:105], v[118:121], v[24:27]
	v_mfma_f32_16x16x32_bf16 v[20:23], v[16:19], v[126:129], v[20:23]
	v_mfma_f32_16x16x32_bf16 v[12:15], v[102:105], v[126:129], v[12:15]
	v_mfma_f32_16x16x32_bf16 v[4:7], v[16:19], v[134:137], v[4:7]
	v_mfma_f32_16x16x32_bf16 v[0:3], v[102:105], v[134:137], v[0:3]
	s_setprio 0
	s_barrier
	s_add_u32 s80, s0, 0x80000
	s_addc_u32 s81, s1, 0
	s_mov_b32 m0, s44
	v_lshl_add_u64 v[8:9], s[80:81], 0, v[74:75]
	v_lshl_add_u64 v[8:9], s[80:81], 0, v[78:79]
	s_mov_b32 m0, s45
	s_nop 0
	s_waitcnt vmcnt(4)
	s_barrier
	s_setprio 1
	s_setprio 0
	s_add_i32 s80, 0, 0x18000
	v_add_u32_e32 v80, s80, v94
	s_barrier
	ds_read_b128 v[8:11], v80
	ds_read_b128 v[16:19], v80 offset:1024
	ds_read_b128 v[98:101], v80 offset:2048
	ds_read_b128 v[102:105], v80 offset:3072
	s_add_u32 s36, s36, 0x180000
	s_addc_u32 s37, s37, 0
	s_mov_b32 m0, s46
	v_lshl_add_u64 v[146:147], s[36:37], 0, v[72:73]
	ds_read_b128 v[106:109], v95 offset:32768
	ds_read_b128 v[110:113], v95 offset:33792
	ds_read_b128 v[114:117], v95 offset:34816
	ds_read_b128 v[118:121], v95 offset:35840
	ds_read_b128 v[122:125], v95 offset:36864
	ds_read_b128 v[126:129], v95 offset:37888
	ds_read_b128 v[130:133], v95 offset:38912
	ds_read_b128 v[134:137], v95 offset:39936
	global_load_lds_dwordx4 v[146:147], off
	v_lshl_add_u64 v[146:147], s[36:37], 0, v[76:77]
	s_mov_b32 m0, s47
	s_nop 0
	global_load_lds_dwordx4 v[146:147], off
	s_waitcnt lgkmcnt(8)
	s_barrier
	s_waitcnt lgkmcnt(0)
	s_setprio 1
	s_waitcnt lgkmcnt(0)
	v_mfma_f32_16x16x32_bf16 v[68:71], v[8:11], v[106:109], v[68:71]
	v_mfma_f32_16x16x32_bf16 v[64:67], v[98:101], v[106:109], v[64:67]
	v_mfma_f32_16x16x32_bf16 v[60:63], v[8:11], v[114:117], v[60:63]
	v_mfma_f32_16x16x32_bf16 v[56:59], v[98:101], v[114:117], v[56:59]
	v_mfma_f32_16x16x32_bf16 v[52:55], v[8:11], v[122:125], v[52:55]
	v_mfma_f32_16x16x32_bf16 v[48:51], v[98:101], v[122:125], v[48:51]
	v_mfma_f32_16x16x32_bf16 v[44:47], v[8:11], v[130:133], v[44:47]
	v_mfma_f32_16x16x32_bf16 v[40:43], v[98:101], v[130:133], v[40:43]
	v_mfma_f32_16x16x32_bf16 v[68:71], v[16:19], v[110:113], v[68:71]
	v_mfma_f32_16x16x32_bf16 v[64:67], v[102:105], v[110:113], v[64:67]
	v_mfma_f32_16x16x32_bf16 v[60:63], v[16:19], v[118:121], v[60:63]
	v_mfma_f32_16x16x32_bf16 v[56:59], v[102:105], v[118:121], v[56:59]
	v_mfma_f32_16x16x32_bf16 v[52:55], v[16:19], v[126:129], v[52:55]
	v_mfma_f32_16x16x32_bf16 v[48:51], v[102:105], v[126:129], v[48:51]
	v_mfma_f32_16x16x32_bf16 v[44:47], v[16:19], v[134:137], v[44:47]
	v_mfma_f32_16x16x32_bf16 v[40:43], v[102:105], v[134:137], v[40:43]
	s_setprio 0
	s_barrier
	s_add_i32 s36, s80, s41
	v_lshl_add_u64 v[106:107], v[138:139], 0, s[6:7]
	s_mov_b32 m0, s36
	s_nop 0
	global_load_lds_dwordx4 v[106:107], off
	v_lshl_add_u64 v[106:107], v[140:141], 0, s[6:7]
	s_add_i32 m0, s36, 0x2000
	s_nop 0
	global_load_lds_dwordx4 v[106:107], off
	s_barrier
	s_waitcnt lgkmcnt(0)
	s_setprio 1
	s_setprio 0
	s_mov_b32 m0, s54
	v_lshl_add_u64 v[138:139], v[142:143], 0, s[8:9]
	s_barrier
	ds_read_b128 v[106:109], v95 offset:49152
	ds_read_b128 v[110:113], v95 offset:50176
	ds_read_b128 v[114:117], v95 offset:51200
	ds_read_b128 v[118:121], v95 offset:52224
	ds_read_b128 v[122:125], v95 offset:53248
	ds_read_b128 v[126:129], v95 offset:54272
	ds_read_b128 v[130:133], v95 offset:55296
	ds_read_b128 v[134:137], v95 offset:56320
	global_load_lds_dwordx4 v[138:139], off
	v_lshl_add_u64 v[138:139], v[144:145], 0, s[8:9]
	s_mov_b32 m0, s55
	s_nop 0
	global_load_lds_dwordx4 v[138:139], off
	s_barrier
	s_waitcnt lgkmcnt(0)
	s_setprio 1
	s_waitcnt lgkmcnt(0)
	v_mfma_f32_16x16x32_bf16 v[36:39], v[8:11], v[106:109], v[36:39]
	v_mfma_f32_16x16x32_bf16 v[32:35], v[98:101], v[106:109], v[32:35]
	v_mfma_f32_16x16x32_bf16 v[28:31], v[8:11], v[114:117], v[28:31]
	v_mfma_f32_16x16x32_bf16 v[24:27], v[98:101], v[114:117], v[24:27]
	v_mfma_f32_16x16x32_bf16 v[20:23], v[8:11], v[122:125], v[20:23]
	v_mfma_f32_16x16x32_bf16 v[12:15], v[98:101], v[122:125], v[12:15]
	v_mfma_f32_16x16x32_bf16 v[4:7], v[8:11], v[130:133], v[4:7]
	v_mfma_f32_16x16x32_bf16 v[0:3], v[98:101], v[130:133], v[0:3]
	v_mfma_f32_16x16x32_bf16 v[36:39], v[16:19], v[110:113], v[36:39]
	v_mfma_f32_16x16x32_bf16 v[32:35], v[102:105], v[110:113], v[32:35]
	v_mfma_f32_16x16x32_bf16 v[28:31], v[16:19], v[118:121], v[28:31]
	v_mfma_f32_16x16x32_bf16 v[24:27], v[102:105], v[118:121], v[24:27]
	v_mfma_f32_16x16x32_bf16 v[20:23], v[16:19], v[126:129], v[20:23]
	v_mfma_f32_16x16x32_bf16 v[12:15], v[102:105], v[126:129], v[12:15]
	v_mfma_f32_16x16x32_bf16 v[4:7], v[16:19], v[134:137], v[4:7]
	v_mfma_f32_16x16x32_bf16 v[0:3], v[102:105], v[134:137], v[0:3]
	s_setprio 0
	s_barrier
	s_add_u32 s0, s0, 0x80080
	s_addc_u32 s1, s1, 0
	s_mov_b32 m0, s56
	v_lshl_add_u64 v[8:9], s[0:1], 0, v[74:75]
	v_lshl_add_u64 v[8:9], s[0:1], 0, v[78:79]
	s_mov_b32 m0, s57
	s_nop 0
	s_waitcnt vmcnt(4)
	s_barrier
	s_setprio 1
	s_setprio 0
	s_add_i32 s79, s79, 2
	s_add_u32 s71, s71, 0x100
	s_addc_u32 s78, s78, 0
	s_add_u32 s34, s34, 0x1800
	s_addc_u32 s35, s35, 0
	s_cmp_gt_u32 s79, 29
	s_barrier
	s_cbranch_scc1 .LBB0_875
